# sample attention: half of the workgroups (blockIdx bit 4) stream the dilation-16 segment before the dilation-4 segment (segswap) on top of v46
# speedup vs baseline: 1.0092x; 1.0092x over previous
; __device__ __forceinline__ float fexp2(float x) { return __builtin_amdgcn_exp2f(x); }
; __device__ __forceinline__ void attn_sample_item(const P& p, int wi, int lane) {
;     ...
;     const int bs = wi >> 5, i = (wi >> 3) & 3, h = wi & 7;
;     const int kg = lane >> 4, li = lane & 15;
;     const int srow = bs * 4 + i;
;     const float* ACC1 = (const float*)(ws + O_ACC1); const float* rstd1 = (const float*)(ws + O_RSTD1);
;     float q[8];
;     { const float rq = rstd1[TP + srow] * (0.08838834764831845f * LOG2E);
;       const f32x4 q0 = acc1_4(ACC1, srow, 3072 + h * 128 + 8 * li), q1 = acc1_4(ACC1, srow, 3072 + h * 128 + 8 * li + 4);
;       q[0] = q0[0] * rq; q[1] = q0[1] * rq; q[2] = q0[2] * rq; q[3] = q0[3] * rq; q[4] = q1[0] * rq; q[5] = q1[1] * rq; q[6] = q1[2] * rq; q[7] = q1[3] * rq; }
;     if (kg == 0) {
;         const float rs = rstd1[TP + srow];
;         float* ko = p.out + OUT_KN + (size_t)srow * 1024 + h * 128 + 8 * li; float* vo = p.out + OUT_VN + (size_t)srow * 1024 + h * 128 + 8 * li;
;         *(f32x4*)ko = acc1_4(ACC1, srow, 4096 + h * 128 + 8 * li) * rs; *(f32x4*)(ko + 4) = acc1_4(ACC1, srow, 4096 + h * 128 + 8 * li + 4) * rs;
;         *(f32x4*)vo = acc1_4(ACC1, srow, 5120 + h * 128 + 8 * li) * rs; *(f32x4*)(vo + 4) = acc1_4(ACC1, srow, 5120 + h * 128 + 8 * li + 4) * rs;
;     }
;     float m = -1e30f, l = 0.f, acc[8];
; #pragma unroll
;     for (int e = 0; e < 8; ++e) acc[e] = 0.f;
;     const float sl = fexp2(-(float)(h + 1)) * LOG2E;
;     for (int g = 0; g < 3; ++g) {
;         const int d = 1 << (2 * g);
; #pragma unroll 3
;         for (int jj = 0; jj < 33; ++jj) {
;             const int j = 4 * jj + kg; const bool valid = j <= 128; const int jc = valid ? j : 128;
;             const int idx = 2048 + i - d * jc;
;             f32x4 k0, k1, v0, v1;
;             if (idx < 2048) { const size_t off = (((size_t)bs * 2048 + idx) * 8 + h) * 128 + 8 * li;
;                 k0 = __builtin_nontemporal_load((const f32x4*)(p.cache_k + off)); k1 = __builtin_nontemporal_load((const f32x4*)(p.cache_k + off + 4)); v0 = __builtin_nontemporal_load((const f32x4*)(p.cache_v + off)); v1 = __builtin_nontemporal_load((const f32x4*)(p.cache_v + off + 4)); }
;             else { const int nr = bs * 4 + (idx - 2048); const float rsn = rstd1[TP + nr]; const int c0 = 4096 + h * 128 + 8 * li;
.Las_item:
	s_ashr_i32 s14, s3, 5
	s_bfe_u32 s15, s3, 0x20003
	s_and_b32 s16, s3, 7
	s_lshl_b32 s17, s14, 2
	s_or_b32 s17, s17, s15
	s_lshl_b32 s18, s14, 23
	s_add_u32 s20, s56, s18
	s_addc_u32 s21, s57, 0
	s_add_u32 s24, s58, s18
	s_addc_u32 s25, s59, 0
	s_lshl_b32 s18, s17, 2
	s_add_u32 s18, s18, 0x8000
	s_load_dword s19, s[10:11], s18
	s_lshl_b32 s23, s16, 9
	v_and_b32_e32 v72, 15, v230
	v_lshlrev_b32_e32 v72, 4, v72
	v_bfe_u32 v73, v230, 4, 2
	v_cvt_f32_u32_e32 v202, v73
	v_add_u32_e32 v72, s23, v72
	s_add_u32 s43, s15, 0x800
	s_lshl_b32 s43, s43, 12
	v_add_u32_e32 v203, s43, v72
	s_sub_u32 s43, 0x7a, s16
	s_lshl_b32 s43, s43, 23
	v_mov_b32_e32 v201, s43
	v_mul_f32_e32 v201, 0xbfb8aa3b, v201
	s_mul_i32 s43, s17, 0x6000
	s_add_u32 s43, s43, 0x3000
	v_add_u32_e32 v64, s43, v72
	v_sub_u32_e32 v67, s15, v73
	v_max_i32_e32 v67, 0, v67
	v_lshl_add_u32 v67, s14, 2, v67
	v_lshlrev_b32_e32 v66, 2, v67
	v_add_u32_e32 v66, 0x8000, v66
	v_mul_u32_u24_e32 v65, 0x6000, v67
	v_add_u32_e32 v65, 0x4000, v65
	v_add_u32_e32 v65, v65, v72
	v_lshlrev_b32_e32 v68, 12, v73
	v_sub_u32_e32 v68, v203, v68
	s_mov_b32 s43, 0x7ff000
	v_add_u32_e32 v69, s43, v72
	v_min_u32_e32 v68, v68, v69
	v_add_u32_e32 v69, 0xfff80000, v203
	global_load_dword v70, v66, s[10:11]
	global_load_dwordx4 v[128:131], v68, s[20:21]
	global_load_dwordx4 v[132:135], v68, s[20:21] offset:256
	global_load_dwordx4 v[136:139], v68, s[24:25]
	global_load_dwordx4 v[140:143], v68, s[24:25] offset:256
	global_load_dwordx4 v[144:147], v69, s[20:21]
	global_load_dwordx4 v[148:151], v69, s[20:21] offset:256
	global_load_dwordx4 v[152:155], v69, s[24:25]
	global_load_dwordx4 v[156:159], v69, s[24:25] offset:256
	v_mov_b32_e32 v71, v64
	global_load_dwordx4 v[0:3], v71, s[8:9]
	v_add_u32_e32 v71, 0x300000, v71
	global_load_dwordx4 v[4:7], v71, s[8:9]
	v_add_u32_e32 v71, 0x300000, v71
	global_load_dwordx4 v[8:11], v71, s[8:9]
	v_add_u32_e32 v71, 0x300000, v71
	global_load_dwordx4 v[12:15], v71, s[8:9]
	v_add_u32_e32 v71, 0x300000, v71
	global_load_dwordx4 v[16:19], v71, s[8:9]
	v_add_u32_e32 v71, 0x300000, v71
	global_load_dwordx4 v[20:23], v71, s[8:9]
	v_add_u32_e32 v71, 0x300000, v71
	global_load_dwordx4 v[24:27], v71, s[8:9]
	v_add_u32_e32 v71, 0x300000, v71
	global_load_dwordx4 v[28:31], v71, s[8:9]
	v_mov_b32_e32 v71, v64
	global_load_dwordx4 v[32:35], v71, s[8:9] offset:256
	v_add_u32_e32 v71, 0x300000, v71
	global_load_dwordx4 v[36:39], v71, s[8:9] offset:256
	v_add_u32_e32 v71, 0x300000, v71
	global_load_dwordx4 v[40:43], v71, s[8:9] offset:256
	v_add_u32_e32 v71, 0x300000, v71
	global_load_dwordx4 v[44:47], v71, s[8:9] offset:256
	v_add_u32_e32 v71, 0x300000, v71
	global_load_dwordx4 v[48:51], v71, s[8:9] offset:256
	v_add_u32_e32 v71, 0x300000, v71
	global_load_dwordx4 v[52:55], v71, s[8:9] offset:256
	v_add_u32_e32 v71, 0x300000, v71
	global_load_dwordx4 v[56:59], v71, s[8:9] offset:256
	v_add_u32_e32 v71, 0x300000, v71
	global_load_dwordx4 v[60:63], v71, s[8:9] offset:256
	s_waitcnt vmcnt(8)
	v_add_f32_e32 v160, v0, v4
	v_add_f32_e32 v161, v1, v5
	v_add_f32_e32 v162, v2, v6
	v_add_f32_e32 v163, v3, v7
	v_add_f32_e32 v160, v160, v8
	v_add_f32_e32 v161, v161, v9
	v_add_f32_e32 v162, v162, v10
	v_add_f32_e32 v163, v163, v11
	v_add_f32_e32 v160, v160, v12
	v_add_f32_e32 v161, v161, v13
	v_add_f32_e32 v162, v162, v14
	v_add_f32_e32 v163, v163, v15
	v_add_f32_e32 v160, v160, v16
	v_add_f32_e32 v161, v161, v17
	v_add_f32_e32 v162, v162, v18
	v_add_f32_e32 v163, v163, v19
	v_add_f32_e32 v160, v160, v20
	v_add_f32_e32 v161, v161, v21
	v_add_f32_e32 v162, v162, v22
	v_add_f32_e32 v163, v163, v23
	v_add_f32_e32 v160, v160, v24
	v_add_f32_e32 v161, v161, v25
	v_add_f32_e32 v162, v162, v26
	v_add_f32_e32 v163, v163, v27
	v_add_f32_e32 v160, v160, v28
	v_add_f32_e32 v161, v161, v29
	v_add_f32_e32 v162, v162, v30
	v_add_f32_e32 v163, v163, v31
	v_mov_b32_e32 v71, v65
	global_load_dwordx4 v[0:3], v71, s[8:9]
	v_add_u32_e32 v71, 0x300000, v71
	global_load_dwordx4 v[4:7], v71, s[8:9]
	v_add_u32_e32 v71, 0x300000, v71
	global_load_dwordx4 v[8:11], v71, s[8:9]
	v_add_u32_e32 v71, 0x300000, v71
	global_load_dwordx4 v[12:15], v71, s[8:9]
	v_add_u32_e32 v71, 0x300000, v71
	global_load_dwordx4 v[16:19], v71, s[8:9]
	v_add_u32_e32 v71, 0x300000, v71
	global_load_dwordx4 v[20:23], v71, s[8:9]
	v_add_u32_e32 v71, 0x300000, v71
	global_load_dwordx4 v[24:27], v71, s[8:9]
	v_add_u32_e32 v71, 0x300000, v71
	global_load_dwordx4 v[28:31], v71, s[8:9]
	s_waitcnt vmcnt(8)
	v_add_f32_e32 v164, v32, v36
	v_add_f32_e32 v165, v33, v37
	v_add_f32_e32 v166, v34, v38
	v_add_f32_e32 v167, v35, v39
	v_add_f32_e32 v164, v164, v40
	v_add_f32_e32 v165, v165, v41
	v_add_f32_e32 v166, v166, v42
	v_add_f32_e32 v167, v167, v43
	v_add_f32_e32 v164, v164, v44
	v_add_f32_e32 v165, v165, v45
	v_add_f32_e32 v166, v166, v46
	v_add_f32_e32 v167, v167, v47
	v_add_f32_e32 v164, v164, v48
	v_add_f32_e32 v165, v165, v49
	v_add_f32_e32 v166, v166, v50
	v_add_f32_e32 v167, v167, v51
	v_add_f32_e32 v164, v164, v52
	v_add_f32_e32 v165, v165, v53
	v_add_f32_e32 v166, v166, v54
	v_add_f32_e32 v167, v167, v55
	v_add_f32_e32 v164, v164, v56
	v_add_f32_e32 v165, v165, v57
	v_add_f32_e32 v166, v166, v58
	v_add_f32_e32 v167, v167, v59
	v_add_f32_e32 v164, v164, v60
	v_add_f32_e32 v165, v165, v61
	v_add_f32_e32 v166, v166, v62
	v_add_f32_e32 v167, v167, v63
	v_mov_b32_e32 v71, v65
	global_load_dwordx4 v[32:35], v71, s[8:9] offset:256
	v_add_u32_e32 v71, 0x300000, v71
	global_load_dwordx4 v[36:39], v71, s[8:9] offset:256
	v_add_u32_e32 v71, 0x300000, v71
	global_load_dwordx4 v[40:43], v71, s[8:9] offset:256
	v_add_u32_e32 v71, 0x300000, v71
	global_load_dwordx4 v[44:47], v71, s[8:9] offset:256
	v_add_u32_e32 v71, 0x300000, v71
	global_load_dwordx4 v[48:51], v71, s[8:9] offset:256
	v_add_u32_e32 v71, 0x300000, v71
	global_load_dwordx4 v[52:55], v71, s[8:9] offset:256
	v_add_u32_e32 v71, 0x300000, v71
	global_load_dwordx4 v[56:59], v71, s[8:9] offset:256
	v_add_u32_e32 v71, 0x300000, v71
	global_load_dwordx4 v[60:63], v71, s[8:9] offset:256
	s_waitcnt vmcnt(8)
; __device__ __forceinline__ f32x4 acc1_4(const float* ACC1, int srow, int col) {
;     f32x4 s = *(const f32x4*)(ACC1 + (size_t)srow * N1 + col);
; #pragma unroll
;     for (int kp = 1; kp < 8; ++kp) s += *(const f32x4*)(ACC1 + ((size_t)kp * TS + srow) * N1 + col);
;     return s;
; __device__ __forceinline__ void attn_sample_item(const P& p, int wi, int lane) {
;     ...
;             else { const int nr = bs * 4 + (idx - 2048); const float rsn = rstd1[TP + nr]; const int c0 = 4096 + h * 128 + 8 * li;
;                 k0 = acc1_4(ACC1, nr, c0) * rsn; k1 = acc1_4(ACC1, nr, c0 + 4) * rsn; v0 = acc1_4(ACC1, nr, c0 + 1024) * rsn; v1 = acc1_4(ACC1, nr, c0 + 1028) * rsn; }
	v_add_f32_e32 v176, v0, v4
	v_add_f32_e32 v177, v1, v5
	v_add_f32_e32 v178, v2, v6
	v_add_f32_e32 v179, v3, v7
	v_add_f32_e32 v176, v176, v8
	v_add_f32_e32 v177, v177, v9
	v_add_f32_e32 v178, v178, v10
	v_add_f32_e32 v179, v179, v11
	v_add_f32_e32 v176, v176, v12
	v_add_f32_e32 v177, v177, v13
	v_add_f32_e32 v178, v178, v14
	v_add_f32_e32 v179, v179, v15
	v_add_f32_e32 v176, v176, v16
	v_add_f32_e32 v177, v177, v17
	v_add_f32_e32 v178, v178, v18
	v_add_f32_e32 v179, v179, v19
	v_add_f32_e32 v176, v176, v20
	v_add_f32_e32 v177, v177, v21
	v_add_f32_e32 v178, v178, v22
	v_add_f32_e32 v179, v179, v23
	v_add_f32_e32 v176, v176, v24
	v_add_f32_e32 v177, v177, v25
	v_add_f32_e32 v178, v178, v26
	v_add_f32_e32 v179, v179, v27
	v_add_f32_e32 v176, v176, v28
	v_add_f32_e32 v177, v177, v29
	v_add_f32_e32 v178, v178, v30
	v_add_f32_e32 v179, v179, v31
	v_add_u32_e32 v71, 0x1000, v65
	global_load_dwordx4 v[0:3], v71, s[8:9]
	v_add_u32_e32 v71, 0x300000, v71
	global_load_dwordx4 v[4:7], v71, s[8:9]
	v_add_u32_e32 v71, 0x300000, v71
	global_load_dwordx4 v[8:11], v71, s[8:9]
	v_add_u32_e32 v71, 0x300000, v71
	global_load_dwordx4 v[12:15], v71, s[8:9]
	v_add_u32_e32 v71, 0x300000, v71
	global_load_dwordx4 v[16:19], v71, s[8:9]
	v_add_u32_e32 v71, 0x300000, v71
	global_load_dwordx4 v[20:23], v71, s[8:9]
	v_add_u32_e32 v71, 0x300000, v71
	global_load_dwordx4 v[24:27], v71, s[8:9]
	v_add_u32_e32 v71, 0x300000, v71
	global_load_dwordx4 v[28:31], v71, s[8:9]
	s_waitcnt vmcnt(8)
	v_add_f32_e32 v180, v32, v36
	v_add_f32_e32 v181, v33, v37
	v_add_f32_e32 v182, v34, v38
	v_add_f32_e32 v183, v35, v39
	v_add_f32_e32 v180, v180, v40
	v_add_f32_e32 v181, v181, v41
	v_add_f32_e32 v182, v182, v42
	v_add_f32_e32 v183, v183, v43
	v_add_f32_e32 v180, v180, v44
	v_add_f32_e32 v181, v181, v45
	v_add_f32_e32 v182, v182, v46
	v_add_f32_e32 v183, v183, v47
	v_add_f32_e32 v180, v180, v48
	v_add_f32_e32 v181, v181, v49
	v_add_f32_e32 v182, v182, v50
	v_add_f32_e32 v183, v183, v51
	v_add_f32_e32 v180, v180, v52
	v_add_f32_e32 v181, v181, v53
	v_add_f32_e32 v182, v182, v54
	v_add_f32_e32 v183, v183, v55
	v_add_f32_e32 v180, v180, v56
	v_add_f32_e32 v181, v181, v57
	v_add_f32_e32 v182, v182, v58
	v_add_f32_e32 v183, v183, v59
	v_add_f32_e32 v180, v180, v60
	v_add_f32_e32 v181, v181, v61
	v_add_f32_e32 v182, v182, v62
	v_add_f32_e32 v183, v183, v63
	v_add_u32_e32 v71, 0x1000, v65
	global_load_dwordx4 v[32:35], v71, s[8:9] offset:256
	v_add_u32_e32 v71, 0x300000, v71
	global_load_dwordx4 v[36:39], v71, s[8:9] offset:256
	v_add_u32_e32 v71, 0x300000, v71
	global_load_dwordx4 v[40:43], v71, s[8:9] offset:256
	v_add_u32_e32 v71, 0x300000, v71
	global_load_dwordx4 v[44:47], v71, s[8:9] offset:256
	v_add_u32_e32 v71, 0x300000, v71
	global_load_dwordx4 v[48:51], v71, s[8:9] offset:256
	v_add_u32_e32 v71, 0x300000, v71
	global_load_dwordx4 v[52:55], v71, s[8:9] offset:256
	v_add_u32_e32 v71, 0x300000, v71
	global_load_dwordx4 v[56:59], v71, s[8:9] offset:256
	v_add_u32_e32 v71, 0x300000, v71
	global_load_dwordx4 v[60:63], v71, s[8:9] offset:256
	s_waitcnt vmcnt(8)
	v_add_f32_e32 v184, v0, v4
	v_add_f32_e32 v185, v1, v5
	v_add_f32_e32 v186, v2, v6
	v_add_f32_e32 v187, v3, v7
	v_add_f32_e32 v184, v184, v8
	v_add_f32_e32 v185, v185, v9
	v_add_f32_e32 v186, v186, v10
	v_add_f32_e32 v187, v187, v11
	v_add_f32_e32 v184, v184, v12
	v_add_f32_e32 v185, v185, v13
	v_add_f32_e32 v186, v186, v14
	v_add_f32_e32 v187, v187, v15
	v_add_f32_e32 v184, v184, v16
	v_add_f32_e32 v185, v185, v17
	v_add_f32_e32 v186, v186, v18
	v_add_f32_e32 v187, v187, v19
	v_add_f32_e32 v184, v184, v20
	v_add_f32_e32 v185, v185, v21
	v_add_f32_e32 v186, v186, v22
	v_add_f32_e32 v187, v187, v23
	v_add_f32_e32 v184, v184, v24
	v_add_f32_e32 v185, v185, v25
	v_add_f32_e32 v186, v186, v26
	v_add_f32_e32 v187, v187, v27
	v_add_f32_e32 v184, v184, v28
	v_add_f32_e32 v185, v185, v29
	v_add_f32_e32 v186, v186, v30
	v_add_f32_e32 v187, v187, v31
	s_waitcnt vmcnt(0)
	v_add_f32_e32 v188, v32, v36
	v_add_f32_e32 v189, v33, v37
	v_add_f32_e32 v190, v34, v38
	v_add_f32_e32 v191, v35, v39
	v_add_f32_e32 v188, v188, v40
	v_add_f32_e32 v189, v189, v41
	v_add_f32_e32 v190, v190, v42
	v_add_f32_e32 v191, v191, v43
	v_add_f32_e32 v188, v188, v44
	v_add_f32_e32 v189, v189, v45
	v_add_f32_e32 v190, v190, v46
	v_add_f32_e32 v191, v191, v47
	v_add_f32_e32 v188, v188, v48
	v_add_f32_e32 v189, v189, v49
	v_add_f32_e32 v190, v190, v50
	v_add_f32_e32 v191, v191, v51
	v_add_f32_e32 v188, v188, v52
	v_add_f32_e32 v189, v189, v53
	v_add_f32_e32 v190, v190, v54
	v_add_f32_e32 v191, v191, v55
	v_add_f32_e32 v188, v188, v56
	v_add_f32_e32 v189, v189, v57
	v_add_f32_e32 v190, v190, v58
	v_add_f32_e32 v191, v191, v59
	v_add_f32_e32 v188, v188, v60
	v_add_f32_e32 v189, v189, v61
	v_add_f32_e32 v190, v190, v62
	v_add_f32_e32 v191, v191, v63
	s_waitcnt lgkmcnt(0)
; __device__ __forceinline__ float fexp2(float x) { return __builtin_amdgcn_exp2f(x); }
; __device__ __forceinline__ void attn_sample_item(const P& p, int wi, int lane) {
;     ...
;     if (kg == 0) {
;         const float rs = rstd1[TP + srow];
;         float* ko = p.out + OUT_KN + (size_t)srow * 1024 + h * 128 + 8 * li; float* vo = p.out + OUT_VN + (size_t)srow * 1024 + h * 128 + 8 * li;
;         *(f32x4*)ko = acc1_4(ACC1, srow, 4096 + h * 128 + 8 * li) * rs; *(f32x4*)(ko + 4) = acc1_4(ACC1, srow, 4096 + h * 128 + 8 * li + 4) * rs;
;         *(f32x4*)vo = acc1_4(ACC1, srow, 5120 + h * 128 + 8 * li) * rs; *(f32x4*)(vo + 4) = acc1_4(ACC1, srow, 5120 + h * 128 + 8 * li + 4) * rs;
;     }
;     float m = -1e30f, l = 0.f, acc[8];
; #pragma unroll
;     for (int e = 0; e < 8; ++e) acc[e] = 0.f;
;     const float sl = fexp2(-(float)(h + 1)) * LOG2E;
;     for (int g = 0; g < 3; ++g) {
;         const int d = 1 << (2 * g);
; #pragma unroll 3
;         for (int jj = 0; jj < 33; ++jj) {
;             const int j = 4 * jj + kg; const bool valid = j <= 128; const int jc = valid ? j : 128;
;             const int idx = 2048 + i - d * jc;
;             f32x4 k0, k1, v0, v1;
;             if (idx < 2048) { const size_t off = (((size_t)bs * 2048 + idx) * 8 + h) * 128 + 8 * li;
;                 k0 = __builtin_nontemporal_load((const f32x4*)(p.cache_k + off)); k1 = __builtin_nontemporal_load((const f32x4*)(p.cache_k + off + 4)); v0 = __builtin_nontemporal_load((const f32x4*)(p.cache_v + off)); v1 = __builtin_nontemporal_load((const f32x4*)(p.cache_v + off + 4)); }
;             else { const int nr = bs * 4 + (idx - 2048); const float rsn = rstd1[TP + nr]; const int c0 = 4096 + h * 128 + 8 * li;
;                 k0 = acc1_4(ACC1, nr, c0) * rsn; k1 = acc1_4(ACC1, nr, c0 + 4) * rsn; v0 = acc1_4(ACC1, nr, c0 + 1024) * rsn; v1 = acc1_4(ACC1, nr, c0 + 1028) * rsn; }
;             float dot = (q[0] * k0[0] + q[1] * k0[1]) + (q[2] * k0[2] + q[3] * k0[3]) + (q[4] * k1[0] + q[5] * k1[1]) + (q[6] * k1[2] + q[7] * k1[3]);
;             dot += __shfl_xor(dot, 1); dot += __shfl_xor(dot, 2); dot += __shfl_xor(dot, 4); dot += __shfl_xor(dot, 8);
;             const float s = valid ? dot - sl * (float)(d * j) : -INFINITY;
	v_mov_b32_e32 v71, s19
	v_mul_f32_e32 v71, 0x3e0293ee, v71
	v_mul_f32_e32 v160, v160, v71
	v_mul_f32_e32 v161, v161, v71
	v_mul_f32_e32 v162, v162, v71
	v_mul_f32_e32 v163, v163, v71
	v_mul_f32_e32 v164, v164, v71
	v_mul_f32_e32 v165, v165, v71
	v_mul_f32_e32 v166, v166, v71
	v_mul_f32_e32 v167, v167, v71
	v_mul_f32_e32 v176, v176, v70
	v_mul_f32_e32 v177, v177, v70
	v_mul_f32_e32 v178, v178, v70
	v_mul_f32_e32 v179, v179, v70
	v_mul_f32_e32 v180, v180, v70
	v_mul_f32_e32 v181, v181, v70
	v_mul_f32_e32 v182, v182, v70
	v_mul_f32_e32 v183, v183, v70
	v_mul_f32_e32 v184, v184, v70
	v_mul_f32_e32 v185, v185, v70
	v_mul_f32_e32 v186, v186, v70
	v_mul_f32_e32 v187, v187, v70
	v_mul_f32_e32 v188, v188, v70
	v_mul_f32_e32 v189, v189, v70
	v_mul_f32_e32 v190, v190, v70
	v_mul_f32_e32 v191, v191, v70
	s_lshl_b32 s43, s17, 12
	v_add_u32_e32 v71, s43, v72
	s_mov_b64 exec, 0xffff
	global_store_dwordx4 v71, v[176:179], s[26:27]
	global_store_dwordx4 v71, v[180:183], s[26:27] offset:256
	global_store_dwordx4 v71, v[184:187], s[28:29]
	global_store_dwordx4 v71, v[188:191], s[28:29] offset:256
	s_mov_b64 exec, -1
	v_cmp_ge_u32_e32 vcc, s15, v73
	s_nop 1
	v_cndmask_b32_e32 v128, v128, v176, vcc
	v_cndmask_b32_e32 v129, v129, v177, vcc
	v_cndmask_b32_e32 v130, v130, v178, vcc
	v_cndmask_b32_e32 v131, v131, v179, vcc
	v_cndmask_b32_e32 v132, v132, v180, vcc
	v_cndmask_b32_e32 v133, v133, v181, vcc
	v_cndmask_b32_e32 v134, v134, v182, vcc
	v_cndmask_b32_e32 v135, v135, v183, vcc
	v_cndmask_b32_e32 v136, v136, v184, vcc
	v_cndmask_b32_e32 v137, v137, v185, vcc
	v_cndmask_b32_e32 v138, v138, v186, vcc
	v_cndmask_b32_e32 v139, v139, v187, vcc
	v_cndmask_b32_e32 v140, v140, v188, vcc
	v_cndmask_b32_e32 v141, v141, v189, vcc
	v_cndmask_b32_e32 v142, v142, v190, vcc
	v_cndmask_b32_e32 v143, v143, v191, vcc
	v_bfe_u32 v183, v230, 4, 2
	v_lshlrev_b32_e32 v195, 12, v183
	v_sub_u32_e32 v195, v203, v195
	s_mov_b32 s42, 0xffffc000
	v_add_u32_e32 v195, s42, v195
	global_load_dwordx4 v[16:19], v195, s[20:21]
	global_load_dwordx4 v[20:23], v195, s[20:21] offset:256
	global_load_dwordx4 v[24:27], v195, s[24:25]
	global_load_dwordx4 v[28:31], v195, s[24:25] offset:256
	v_add_u32_e32 v195, s42, v195
	global_load_dwordx4 v[32:35], v195, s[20:21]
	global_load_dwordx4 v[36:39], v195, s[20:21] offset:256
	global_load_dwordx4 v[40:43], v195, s[24:25]
	global_load_dwordx4 v[44:47], v195, s[24:25] offset:256
	v_add_u32_e32 v195, s42, v195
	global_load_dwordx4 v[48:51], v195, s[20:21]
	global_load_dwordx4 v[52:55], v195, s[20:21] offset:256
	global_load_dwordx4 v[56:59], v195, s[24:25]
	global_load_dwordx4 v[60:63], v195, s[24:25] offset:256
	v_add_u32_e32 v195, s42, v195
	global_load_dwordx4 v[64:67], v195, s[20:21]
	global_load_dwordx4 v[68:71], v195, s[20:21] offset:256
	global_load_dwordx4 v[72:75], v195, s[24:25]
	global_load_dwordx4 v[76:79], v195, s[24:25] offset:256
	v_add_u32_e32 v195, s42, v195
	global_load_dwordx4 v[80:83], v195, s[20:21]
	global_load_dwordx4 v[84:87], v195, s[20:21] offset:256
	global_load_dwordx4 v[88:91], v195, s[24:25]
	global_load_dwordx4 v[92:95], v195, s[24:25] offset:256
	v_add_u32_e32 v195, s42, v195
	global_load_dwordx4 v[96:99], v195, s[20:21]
	global_load_dwordx4 v[100:103], v195, s[20:21] offset:256
	global_load_dwordx4 v[104:107], v195, s[24:25]
	global_load_dwordx4 v[108:111], v195, s[24:25] offset:256
	v_add_u32_e32 v195, s42, v195
	global_load_dwordx4 v[112:115], v195, s[20:21]
	global_load_dwordx4 v[116:119], v195, s[20:21] offset:256
	global_load_dwordx4 v[120:123], v195, s[24:25]
	global_load_dwordx4 v[124:127], v195, s[24:25] offset:256
	v_add_u32_e32 v195, s42, v195
	global_load_dwordx4 v[0:3], v195, s[20:21]
	global_load_dwordx4 v[4:7], v195, s[20:21] offset:256
	global_load_dwordx4 v[8:11], v195, s[24:25]
	global_load_dwordx4 v[12:15], v195, s[24:25] offset:256
	v_lshlrev_b32_e32 v176, 14, v183
	v_sub_u32_e32 v176, v203, v176
	v_add_u32_e32 v176, 0xc000, v176
	v_lshlrev_b32_e32 v177, 16, v183
	v_sub_u32_e32 v177, v203, v177
	v_add_u32_e32 v177, 0x30000, v177
	v_add_f32_e32 v182, 1.0, v202
	v_mul_f32_e32 v182, v182, v201
	v_mul_f32_e32 v178, 4.0, v182
	v_mul_f32_e32 v179, 16.0, v182
	v_mul_f32_e32 v180, 16.0, v201
	v_mul_f32_e32 v181, 64.0, v201
	v_mul_f32_e32 v196, 4.0, v201
	s_bitcmp1_b32 s2, 4
	s_cbranch_scc0 .Las_noswap
	v_swap_b32 v176, v177
	v_swap_b32 v178, v179
	v_swap_b32 v180, v181
; __device__ __forceinline__ float fexp2(float x) { return __builtin_amdgcn_exp2f(x); }
; __device__ __forceinline__ void attn_sample_item(const P& p, int wi, int lane) {
;     ...
;     float m = -1e30f, l = 0.f, acc[8];
; #pragma unroll
;     for (int e = 0; e < 8; ++e) acc[e] = 0.f;
;     const float sl = fexp2(-(float)(h + 1)) * LOG2E;
;     for (int g = 0; g < 3; ++g) {
;         const int d = 1 << (2 * g);
; #pragma unroll 3
;         for (int jj = 0; jj < 33; ++jj) {
;             const int j = 4 * jj + kg; const bool valid = j <= 128; const int jc = valid ? j : 128;
;             const int idx = 2048 + i - d * jc;
;             f32x4 k0, k1, v0, v1;
;             if (idx < 2048) { const size_t off = (((size_t)bs * 2048 + idx) * 8 + h) * 128 + 8 * li;
;                 k0 = __builtin_nontemporal_load((const f32x4*)(p.cache_k + off)); k1 = __builtin_nontemporal_load((const f32x4*)(p.cache_k + off + 4)); v0 = __builtin_nontemporal_load((const f32x4*)(p.cache_v + off)); v1 = __builtin_nontemporal_load((const f32x4*)(p.cache_v + off + 4)); }
;             else { const int nr = bs * 4 + (idx - 2048); const float rsn = rstd1[TP + nr]; const int c0 = 4096 + h * 128 + 8 * li;
;                 k0 = acc1_4(ACC1, nr, c0) * rsn; k1 = acc1_4(ACC1, nr, c0 + 4) * rsn; v0 = acc1_4(ACC1, nr, c0 + 1024) * rsn; v1 = acc1_4(ACC1, nr, c0 + 1028) * rsn; }
;             float dot = (q[0] * k0[0] + q[1] * k0[1]) + (q[2] * k0[2] + q[3] * k0[3]) + (q[4] * k1[0] + q[5] * k1[1]) + (q[6] * k1[2] + q[7] * k1[3]);
;             dot += __shfl_xor(dot, 1); dot += __shfl_xor(dot, 2); dot += __shfl_xor(dot, 4); dot += __shfl_xor(dot, 8);
;             const float s = valid ? dot - sl * (float)(d * j) : -INFINITY;
;             const float mn = fmaxf(m, s), sc = fexp2(m - mn), pe = fexp2(s - mn);
;             l = l * sc + pe;
;             acc[0] = acc[0] * sc + pe * v0[0]; acc[1] = acc[1] * sc + pe * v0[1]; acc[2] = acc[2] * sc + pe * v0[2]; acc[3] = acc[3] * sc + pe * v0[3];
;             acc[4] = acc[4] * sc + pe * v1[0]; acc[5] = acc[5] * sc + pe * v1[1]; acc[6] = acc[6] * sc + pe * v1[2]; acc[7] = acc[7] * sc + pe * v1[3];
;             m = mn;
;         }
.Las_noswap:
	v_mov_b32_e32 v192, 0xf149f2ca
	v_mov_b32_e32 v193, 0
	v_mov_b32_e32 v168, 0
	v_mov_b32_e32 v169, 0
	v_mov_b32_e32 v170, 0
	v_mov_b32_e32 v171, 0
	v_mov_b32_e32 v172, 0
	v_mov_b32_e32 v173, 0
	v_mov_b32_e32 v174, 0
	v_mov_b32_e32 v175, 0
	v_mul_f32_e32 v194, v201, v202
	v_mov_b32_e32 v182, 0x3dcae00d
	v_cmp_eq_u32_e32 vcc, 0, v183
	s_nop 1
	v_cndmask_b32_e32 v194, v194, v182, vcc
	v_fma_f32 v197, v160, v128, v194
	v_fmac_f32_e32 v197, v161, v129
	v_fmac_f32_e32 v197, v162, v130
	v_fmac_f32_e32 v197, v163, v131
	v_fmac_f32_e32 v197, v164, v132
	v_fmac_f32_e32 v197, v165, v133
	v_fmac_f32_e32 v197, v166, v134
	v_fmac_f32_e32 v197, v167, v135
	s_nop 1
	v_add_f32_dpp v197, v197, v197 row_ror:8 row_mask:0xf bank_mask:0xf
	s_nop 1
	v_add_f32_dpp v197, v197, v197 row_ror:4 row_mask:0xf bank_mask:0xf
	s_nop 1
	v_add_f32_dpp v197, v197, v197 row_ror:2 row_mask:0xf bank_mask:0xf
	s_nop 1
	v_add_f32_dpp v197, v197, v197 row_ror:1 row_mask:0xf bank_mask:0xf
	v_max_f32_e32 v198, v192, v197
	v_sub_f32_e32 v199, v192, v198
	v_sub_f32_e32 v200, v197, v198
	v_exp_f32_e32 v199, v199
	v_exp_f32_e32 v200, v200
	v_mov_b32_e32 v192, v198
	v_fma_f32 v193, v193, v199, v200
	v_mul_f32_e32 v168, v168, v199
	v_mul_f32_e32 v169, v169, v199
	v_mul_f32_e32 v170, v170, v199
	v_mul_f32_e32 v171, v171, v199
	v_mul_f32_e32 v172, v172, v199
	v_mul_f32_e32 v173, v173, v199
	v_mul_f32_e32 v174, v174, v199
	v_mul_f32_e32 v175, v175, v199
	v_fmac_f32_e32 v168, v200, v136
	v_fmac_f32_e32 v169, v200, v137
	v_fmac_f32_e32 v170, v200, v138
	v_fmac_f32_e32 v171, v200, v139
	v_fmac_f32_e32 v172, v200, v140
	v_fmac_f32_e32 v173, v200, v141
	v_fmac_f32_e32 v174, v200, v142
	v_fmac_f32_e32 v175, v200, v143
	v_mul_f32_e32 v194, 0x43000000, v201
	v_mov_b32_e32 v182, 0xff800000
	v_cndmask_b32_e32 v194, v182, v194, vcc
	v_fma_f32 v197, v160, v144, v194
	v_fmac_f32_e32 v197, v161, v145
	v_fmac_f32_e32 v197, v162, v146
	v_fmac_f32_e32 v197, v163, v147
	v_fmac_f32_e32 v197, v164, v148
	v_fmac_f32_e32 v197, v165, v149
	v_fmac_f32_e32 v197, v166, v150
	v_fmac_f32_e32 v197, v167, v151
	s_nop 1
	v_add_f32_dpp v197, v197, v197 row_ror:8 row_mask:0xf bank_mask:0xf
	s_nop 1
	v_add_f32_dpp v197, v197, v197 row_ror:4 row_mask:0xf bank_mask:0xf
	s_nop 1
	v_add_f32_dpp v197, v197, v197 row_ror:2 row_mask:0xf bank_mask:0xf
	s_nop 1
	v_add_f32_dpp v197, v197, v197 row_ror:1 row_mask:0xf bank_mask:0xf
	v_max_f32_e32 v198, v192, v197
	v_sub_f32_e32 v199, v192, v198
	v_sub_f32_e32 v200, v197, v198
	v_exp_f32_e32 v199, v199
	v_exp_f32_e32 v200, v200
	v_mov_b32_e32 v192, v198
	v_fma_f32 v193, v193, v199, v200
	v_mul_f32_e32 v168, v168, v199
	v_mul_f32_e32 v169, v169, v199
	v_mul_f32_e32 v170, v170, v199
	v_mul_f32_e32 v171, v171, v199
	v_mul_f32_e32 v172, v172, v199
	v_mul_f32_e32 v173, v173, v199
	v_mul_f32_e32 v174, v174, v199
	v_mul_f32_e32 v175, v175, v199
	v_fmac_f32_e32 v168, v200, v152
	v_fmac_f32_e32 v169, v200, v153
	v_fmac_f32_e32 v170, v200, v154
	v_fmac_f32_e32 v171, v200, v155
	v_fmac_f32_e32 v172, v200, v156
	v_fmac_f32_e32 v173, v200, v157
	v_fmac_f32_e32 v174, v200, v158
	v_fmac_f32_e32 v175, v200, v159
	v_add_f32_e32 v194, 4.0, v202
	v_mul_f32_e32 v194, v194, v201
	s_mov_b32 s33, 0
	s_branch .Las_slot1
.Las_tripA:
	s_cmp_eq_u32 s33, 3
	s_cbranch_scc0 .Las_sw1A
	v_mov_b32_e32 v195, v176
	s_mov_b32 s42, 0xffff0000
	s_bitcmp1_b32 s2, 4
	s_cbranch_scc0 .Las_sw1A
	s_mov_b32 s42, 0xfffc0000
.Las_sw1A:
	s_cmp_eq_u32 s33, 7
	s_cbranch_scc0 .Las_sw2A
	v_mov_b32_e32 v195, v177
	s_mov_b32 s42, 0xfffc0000
	s_bitcmp1_b32 s2, 4
	s_cbranch_scc0 .Las_sw2A
	s_mov_b32 s42, 0xffff0000
